# combo1 + ph3: wave 0 (S5 scan walker) excluded from retention scan and Toeplitz fill
# speedup vs baseline: 1.0058x; 1.0058x over previous
; __device__ __forceinline__ float ret_log2g(int h) { return log1pf(-exp2f(-5.f - (float)h)) * 1.4426950408889634f; }
; __device__ __forceinline__ void ret_scan_phase(const Frame& F, const float* KV, bf16* RT) {
;     for (int idx = F.bx * NTHR + F.tid; idx < 64 * 4096; idx += F.G * NTHR) { const int bh = idx >> 12, el = idx & 4095, h = bh & 7; const float cd = exp2f(128.f * ret_log2g(h));
;         float r = 0.f; const float* kv = KV + (size_t)bh * 32 * 4096 + el; bf16* rt = RT + (size_t)bh * 32 * 4096 + el; float k[32];
.LBB0_352:
	s_mul_i32 s1, s96, 0x1c0
	v_add_u32_e32 v1, s1, v56
	v_subrev_u32_e32 v1, 64, v1
	v_mov_b32_e32 v3, 0x7fffffff
	v_cmp_gt_u32_e32 vcc, 64, v56
	v_cndmask_b32_e32 v1, v1, v3, vcc
	s_mov_b32 s0, 0x40000
	v_cmp_gt_i32_e32 vcc, s0, v1
	s_and_saveexec_b64 s[4:5], vcc
	s_cbranch_execz .LBB0_355
	s_add_u32 s6, s78, 0xbc00000
	s_addc_u32 s7, s79, 0
	s_add_u32 s8, s78, 0xdc00000
	s_addc_u32 s9, s79, 0
	s_mul_i32 s1, s82, 0x1c0
	s_mov_b64 s[10:11], 0
	s_mov_b32 s2, 0xc2fc0000
	v_mov_b32_e32 v6, 0x42800000
	v_not_b32_e32 v7, 63
	s_mov_b32 s3, 0x3f2aaaab
	v_mov_b32_e32 v8, 0x3ecc95a3
	s_mov_b32 s12, 0x3f317218
	v_mov_b32_e32 v9, 0x7fc00000
	v_mov_b32_e32 v10, 0xff800000
	s_mov_b32 s13, 0x33800000
	v_mov_b32_e32 v3, 0
	s_movk_i32 s14, 0x4000
	s_mov_b32 s15, 0x8000
	s_mov_b32 s16, 0xc000
	s_mov_b32 s17, 0x10000
	s_mov_b32 s18, 0x14000
	s_mov_b32 s19, 0x18000
	s_mov_b32 s20, 0x1c000
	s_mov_b32 s21, 0x20000
	s_mov_b32 s22, 0x24000
	s_mov_b32 s23, 0x28000
	s_mov_b32 s24, 0x2c000
	s_mov_b32 s25, 0x30000
	s_mov_b32 s26, 0x34000
	s_mov_b32 s27, 0x38000
	s_mov_b32 s28, 0x3c000
	s_mov_b32 s29, 0x44000
	s_mov_b32 s30, 0x48000
	s_mov_b32 s31, 0x4c000
	s_mov_b32 s33, 0x50000
	s_mov_b32 s34, 0x54000
	s_mov_b32 s35, 0x58000
	s_mov_b32 s36, 0x5c000
	s_mov_b32 s37, 0x60000
	s_mov_b32 s38, 0x64000
	s_mov_b32 s39, 0x68000
	s_mov_b32 s40, 0x6c000
	s_mov_b32 s41, 0x70000
	s_mov_b32 s42, 0x74000
	s_mov_b32 s43, 0x78000
	s_movk_i32 s44, 0x7fff
	s_movk_i32 s45, 0x2000
	s_movk_i32 s46, 0x6000
	s_mov_b32 s47, 0xa000
	s_mov_b32 s48, 0xe000
	s_mov_b32 s49, 0x12000
	s_mov_b32 s50, 0x16000
	s_mov_b32 s51, 0x1a000
	s_mov_b32 s52, 0x1e000
	s_mov_b32 s53, 0x22000
	s_mov_b32 s54, 0x26000
	s_mov_b32 s55, 0x2a000
	s_mov_b32 s56, 0x2e000
	s_mov_b32 s57, 0x32000
	s_mov_b32 s58, 0x36000
	s_mov_b32 s59, 0x3ffff
	v_mov_b32_e32 v11, v1

; __device__ __forceinline__ void s5_fill_T(const Frame& F, const float* KMAT, bf16* WYT) {
;     for (int it = F.bx * NTHR + F.tid; it < 32 * 512 * 64; it += F.G * NTHR) { const int k0 = (it & 63) * 8, n = (it >> 6) & 511, g = it >> 15; const int sg = k0 >> 4, c0 = k0 & 15, tau = n >> 4, cp = n & 15;
;         v4u w = {0u, 0u, 0u, 0u};
.LBB0_355:
	s_or_b64 exec, exec, s[4:5]
	s_mov_b32 s0, 0x100000
	v_cmp_gt_i32_e32 vcc, s0, v1
	s_and_saveexec_b64 s[4:5], vcc
	s_cbranch_execz .LBB0_360
	s_add_u32 s6, s78, 0x200000
	s_addc_u32 s7, s79, 0
	s_add_u32 s10, s78, 0xc00000
	s_addc_u32 s11, s79, 0
	v_lshlrev_b32_e32 v2, 3, v56
	s_mul_i32 s0, s82, 0x1c0
	v_lshlrev_b32_e32 v10, 3, v1
	s_mul_i32 s1, s82, 0xe00
	s_mov_b64 s[8:9], 0
	v_mov_b32_e32 v7, 0
	s_movk_i32 s2, 0x7fff
	s_mov_b32 s3, 0xffff0000
	s_movk_i32 s12, 0x500
	v_mov_b64_e32 v[8:9], s[10:11]
	s_mov_b32 s13, 0xfffff
	s_branch .LBB0_358
